# fused out-projection epilogue: first row statistic's 16 dependent ds_bpermute round trips batched 4 groups at a time; residual-row waits count the asm stores (vmcnt(15))
# speedup vs baseline: 1.0086x; 1.0038x over previous
.LBB0_498:
	v_lshlrev_b32_e32 v138, 2, v218
	v_xor_b32_e32 v236, 64, v138
	v_xor_b32_e32 v237, 0x80, v138
	s_lshl_b32 s6, s41, 2
	v_cmp_gt_u32_e64 s[4:5], 16, v218
	s_add_i32 s9, s6, 0
	s_lshl_b32 s22, s40, 10
	s_add_i32 s22, s9, s22
	v_lshl_add_u32 v140, v1, 4, s22
	v_mul_f32_e32 v244, v127, v127
	v_mul_f32_e32 v141, v129, v129
	v_fmac_f32_e32 v244, v126, v126
	v_fmac_f32_e32 v141, v128, v128
	v_add_f32_e32 v244, v244, v141
	v_mul_f32_e32 v139, v123, v123
	v_mul_f32_e32 v141, v125, v125
	v_fmac_f32_e32 v139, v122, v122
	v_fmac_f32_e32 v141, v124, v124
	v_add_f32_e32 v139, v139, v141
	v_add_f32_e32 v244, v139, v244
	v_mul_f32_e32 v139, v119, v119
	v_mul_f32_e32 v141, v121, v121
	v_fmac_f32_e32 v139, v118, v118
	v_fmac_f32_e32 v141, v120, v120
	v_add_f32_e32 v139, v139, v141
	v_add_f32_e32 v244, v139, v244
	v_mul_f32_e32 v139, v115, v115
	v_mul_f32_e32 v141, v117, v117
	v_fmac_f32_e32 v139, v114, v114
	v_fmac_f32_e32 v141, v116, v116
	v_add_f32_e32 v139, v139, v141
	v_add_f32_e32 v244, v139, v244
	v_mul_f32_e32 v245, v111, v111
	v_mul_f32_e32 v141, v113, v113
	v_fmac_f32_e32 v245, v110, v110
	v_fmac_f32_e32 v141, v112, v112
	v_add_f32_e32 v245, v245, v141
	v_mul_f32_e32 v139, v107, v107
	v_mul_f32_e32 v141, v109, v109
	v_fmac_f32_e32 v139, v106, v106
	v_fmac_f32_e32 v141, v108, v108
	v_add_f32_e32 v139, v139, v141
	v_add_f32_e32 v245, v139, v245
	v_mul_f32_e32 v139, v103, v103
	v_mul_f32_e32 v141, v105, v105
	v_fmac_f32_e32 v139, v102, v102
	v_fmac_f32_e32 v141, v104, v104
	v_add_f32_e32 v139, v139, v141
	v_add_f32_e32 v245, v139, v245
	v_mul_f32_e32 v139, v99, v99
	v_mul_f32_e32 v141, v101, v101
	v_fmac_f32_e32 v139, v98, v98
	v_fmac_f32_e32 v141, v100, v100
	v_add_f32_e32 v139, v139, v141
	v_add_f32_e32 v245, v139, v245
	v_mul_f32_e32 v246, v95, v95
	v_mul_f32_e32 v141, v97, v97
	v_fmac_f32_e32 v246, v94, v94
	v_fmac_f32_e32 v141, v96, v96
	v_add_f32_e32 v246, v246, v141
	v_mul_f32_e32 v139, v91, v91
	v_mul_f32_e32 v141, v93, v93
	v_fmac_f32_e32 v139, v90, v90
	v_fmac_f32_e32 v141, v92, v92
	v_add_f32_e32 v139, v139, v141
	v_add_f32_e32 v246, v139, v246
	v_mul_f32_e32 v139, v87, v87
	v_mul_f32_e32 v141, v89, v89
	v_fmac_f32_e32 v139, v86, v86
	v_fmac_f32_e32 v141, v88, v88
	v_add_f32_e32 v139, v139, v141
	v_add_f32_e32 v246, v139, v246
	v_mul_f32_e32 v139, v83, v83
	v_mul_f32_e32 v141, v85, v85
	v_fmac_f32_e32 v139, v82, v82
	v_fmac_f32_e32 v141, v84, v84
	v_add_f32_e32 v139, v139, v141
	v_add_f32_e32 v246, v139, v246
	v_mul_f32_e32 v247, v79, v79
	v_mul_f32_e32 v141, v81, v81
	v_fmac_f32_e32 v247, v78, v78
	v_fmac_f32_e32 v141, v80, v80
	v_add_f32_e32 v247, v247, v141
	v_mul_f32_e32 v139, v75, v75
	v_mul_f32_e32 v141, v77, v77
	v_fmac_f32_e32 v139, v74, v74
	v_fmac_f32_e32 v141, v76, v76
	v_add_f32_e32 v139, v139, v141
	v_add_f32_e32 v247, v139, v247
	v_mul_f32_e32 v139, v71, v71
	v_mul_f32_e32 v141, v73, v73
	v_fmac_f32_e32 v139, v70, v70
	v_fmac_f32_e32 v141, v72, v72
	v_add_f32_e32 v139, v139, v141
	v_add_f32_e32 v247, v139, v247
	v_mul_f32_e32 v139, v67, v67
	v_mul_f32_e32 v141, v69, v69
	v_fmac_f32_e32 v139, v66, v66
	v_fmac_f32_e32 v141, v68, v68
	v_add_f32_e32 v139, v139, v141
	v_add_f32_e32 v247, v139, v247
	ds_bpermute_b32 v248, v236, v244
	ds_bpermute_b32 v249, v236, v245
	ds_bpermute_b32 v250, v236, v246
	ds_bpermute_b32 v251, v236, v247
	s_waitcnt lgkmcnt(0)
	v_add_f32_e32 v244, v244, v248
	v_add_f32_e32 v245, v245, v249
	v_add_f32_e32 v246, v246, v250
	v_add_f32_e32 v247, v247, v251
	ds_bpermute_b32 v248, v237, v244
	ds_bpermute_b32 v249, v237, v245
	ds_bpermute_b32 v250, v237, v246
	ds_bpermute_b32 v251, v237, v247
	s_waitcnt lgkmcnt(0)
	s_and_saveexec_b64 s[6:7], s[4:5]
	v_add_f32_e32 v244, v244, v248
	v_add_f32_e32 v245, v245, v249
	v_add_f32_e32 v246, v246, v250
	v_add_f32_e32 v247, v247, v251
	ds_write_b32 v140, v244
	ds_write_b32 v140, v245 offset:256
	ds_write_b32 v140, v246 offset:512
	ds_write_b32 v140, v247 offset:768
	s_or_b64 exec, exec, s[6:7]
	v_mul_f32_e32 v244, v63, v63
	v_mul_f32_e32 v141, v65, v65
	v_fmac_f32_e32 v244, v62, v62
	v_fmac_f32_e32 v141, v64, v64
	v_add_f32_e32 v244, v244, v141
	v_mul_f32_e32 v139, v59, v59
	v_mul_f32_e32 v141, v61, v61
	v_fmac_f32_e32 v139, v58, v58
	v_fmac_f32_e32 v141, v60, v60
	v_add_f32_e32 v139, v139, v141
	v_add_f32_e32 v244, v139, v244
	v_mul_f32_e32 v139, v55, v55
	v_mul_f32_e32 v141, v57, v57
	v_fmac_f32_e32 v139, v54, v54
	v_fmac_f32_e32 v141, v56, v56
	v_add_f32_e32 v139, v139, v141
	v_add_f32_e32 v244, v139, v244
	v_mul_f32_e32 v139, v51, v51
	v_mul_f32_e32 v141, v53, v53
	v_fmac_f32_e32 v139, v50, v50
	v_fmac_f32_e32 v141, v52, v52
	v_add_f32_e32 v139, v139, v141
	v_add_f32_e32 v244, v139, v244
	v_mul_f32_e32 v245, v47, v47
	v_mul_f32_e32 v141, v49, v49
	v_fmac_f32_e32 v245, v46, v46
	v_fmac_f32_e32 v141, v48, v48
	v_add_f32_e32 v245, v245, v141
	v_mul_f32_e32 v139, v43, v43
	v_mul_f32_e32 v141, v45, v45
	v_fmac_f32_e32 v139, v42, v42
	v_fmac_f32_e32 v141, v44, v44
	v_add_f32_e32 v139, v139, v141
	v_add_f32_e32 v245, v139, v245
	v_mul_f32_e32 v139, v39, v39
	v_mul_f32_e32 v141, v41, v41
	v_fmac_f32_e32 v139, v38, v38
	v_fmac_f32_e32 v141, v40, v40
	v_add_f32_e32 v139, v139, v141
	v_add_f32_e32 v245, v139, v245
	v_mul_f32_e32 v139, v35, v35
	v_mul_f32_e32 v141, v37, v37
	v_fmac_f32_e32 v139, v34, v34
	v_fmac_f32_e32 v141, v36, v36
	v_add_f32_e32 v139, v139, v141
	v_add_f32_e32 v245, v139, v245
	v_mul_f32_e32 v246, v31, v31
	v_mul_f32_e32 v141, v33, v33
	v_fmac_f32_e32 v246, v30, v30
	v_fmac_f32_e32 v141, v32, v32
	v_add_f32_e32 v246, v246, v141
	v_mul_f32_e32 v139, v27, v27
	v_mul_f32_e32 v141, v29, v29
	v_fmac_f32_e32 v139, v26, v26
	v_fmac_f32_e32 v141, v28, v28
	v_add_f32_e32 v139, v139, v141
	v_add_f32_e32 v246, v139, v246
	v_mul_f32_e32 v139, v23, v23
	v_mul_f32_e32 v141, v25, v25
	v_fmac_f32_e32 v139, v22, v22
	v_fmac_f32_e32 v141, v24, v24
	v_add_f32_e32 v139, v139, v141
	v_add_f32_e32 v246, v139, v246
	v_mul_f32_e32 v139, v19, v19
	v_mul_f32_e32 v141, v21, v21
	v_fmac_f32_e32 v139, v18, v18
	v_fmac_f32_e32 v141, v20, v20
	v_add_f32_e32 v139, v139, v141
	v_add_f32_e32 v246, v139, v246
	v_mul_f32_e32 v247, v15, v15
	v_mul_f32_e32 v141, v17, v17
	v_fmac_f32_e32 v247, v14, v14
	v_fmac_f32_e32 v141, v16, v16
	v_add_f32_e32 v247, v247, v141
	v_mul_f32_e32 v139, v11, v11
	v_mul_f32_e32 v141, v13, v13
	v_fmac_f32_e32 v139, v10, v10
	v_fmac_f32_e32 v141, v12, v12
	v_add_f32_e32 v139, v139, v141
	v_add_f32_e32 v247, v139, v247
	v_mul_f32_e32 v139, v7, v7
	v_mul_f32_e32 v141, v9, v9
	v_fmac_f32_e32 v139, v6, v6
	v_fmac_f32_e32 v141, v8, v8
	v_add_f32_e32 v139, v139, v141
	v_add_f32_e32 v247, v139, v247
	v_mul_f32_e32 v139, v3, v3
	v_mul_f32_e32 v141, v5, v5
	v_fmac_f32_e32 v139, v2, v2
	v_fmac_f32_e32 v141, v4, v4
	v_add_f32_e32 v139, v139, v141
	v_add_f32_e32 v247, v139, v247
	ds_bpermute_b32 v248, v236, v244
	ds_bpermute_b32 v249, v236, v245
	ds_bpermute_b32 v250, v236, v246
	ds_bpermute_b32 v251, v236, v247
	s_waitcnt lgkmcnt(0)
	v_add_f32_e32 v244, v244, v248
	v_add_f32_e32 v245, v245, v249
	v_add_f32_e32 v246, v246, v250
	v_add_f32_e32 v247, v247, v251
	ds_bpermute_b32 v248, v237, v244
	ds_bpermute_b32 v249, v237, v245
	ds_bpermute_b32 v250, v237, v246
	ds_bpermute_b32 v251, v237, v247
	s_waitcnt lgkmcnt(0)
	s_and_saveexec_b64 s[6:7], s[4:5]
	v_add_f32_e32 v244, v244, v248
	v_add_f32_e32 v245, v245, v249
	v_add_f32_e32 v246, v246, v250
	v_add_f32_e32 v247, v247, v251
	ds_write_b32 v140, v244 offset:2048
	ds_write_b32 v140, v245 offset:2304
	ds_write_b32 v140, v246 offset:2560
	ds_write_b32 v140, v247 offset:2816
	s_or_b64 exec, exec, s[6:7]
	s_and_b64 s[6:7], s[16:17], exec
	s_cselect_b32 s9, 2, 3
	s_and_b64 s[6:7], s[20:21], exec
	s_cselect_b32 s9, 1, s9
	s_and_b64 s[6:7], exec, s[18:19]
	v_readlane_b32 s6, v254, 51
	s_cselect_b32 s9, 0, s9
	s_lshl_b32 s6, s6, 1
	s_add_i32 s16, s6, 6
	s_lshl_b32 s17, s9, 1
	s_and_b64 s[6:7], s[10:11], exec
	s_cselect_b32 s6, s17, s16
	s_lshl_b32 s6, s6, 18
	v_and_b32_e32 v138, 31, v233
	s_and_b32 s6, s6, 0x180000
	v_lshl_or_b32 v142, s13, 5, v138
	s_add_u32 s6, s0, s6
	v_add_u32_e32 v138, s8, v142
	s_addc_u32 s7, s1, 0
	s_waitcnt lgkmcnt(0)
	s_barrier
	s_waitcnt lgkmcnt(0)
	v_ashrrev_i32_e32 v139, 31, v138
	v_lshl_add_u64 v[138:139], v[138:139], 3, s[6:7]
	s_mov_b64 s[6:7], 0x100000
	v_lshl_add_u64 v[138:139], v[138:139], 0, s[6:7]
	v_cmp_gt_u32_e64 s[6:7], 32, v218
	s_and_saveexec_b64 s[16:17], s[6:7]
	s_cbranch_execz .LBB0_516
	v_lshl_add_u32 v140, v142, 4, 0
	ds_read_b128 v[152:155], v140
	s_mov_b32 s13, 0x3d000000
	s_waitcnt lgkmcnt(0)
	v_add_f32_e32 v140, v152, v153
	v_add_f32_e32 v141, v154, v155
	v_add_f32_e32 v140, v140, v141
	v_min_f32_e32 v140, 0x4f6e6b28, v140
	v_mul_f32_e32 v141, 0x3d000000, v140
	v_floor_f32_e32 v141, v141
	v_fma_f32 v140, v140, s13, -v141
	v_mul_f32_e32 v140, 0x4e000000, v140
	v_cvt_u32_f32_e32 v140, v140
	v_cvt_u32_f32_e32 v141, v141
	v_lshl_or_b32 v140, v140, 3, 1
	global_atomic_add_x2 v[138:139], v[140:141], off
